# up-projection epilogue: the eight row-sum loads of a tile issued together at the first row block instead of one load + full wait per block
# baseline (speedup 1.0000x reference)
;     __device__ __forceinline__ void operator()(const f32x4 (&acc)[2][2][4][2], const Unit& u, int wr, int wc, int fr, int fq) const {
;         const int row0 = u.pm * BM + wr * 64 + fr, col0 = u.pn * BM + wc * 32 + 8 * fq;
; #pragma unroll
;         for (int ai = 0; ai < 2; ++ai)
; #pragma unroll
;             for (int m = 0; m < 4; ++m) {
;                 const size_t row = (size_t)(row0 + ai * HALF + m * 16);
;                 const float rs = ss ? rsqrtf(ss[row] * (1.f / 1024.f) + 1e-6f) : 1.f;
.LBB0_640:
	v_readlane_b32 s12, v245, 26
	v_readlane_b32 s13, v245, 27
	v_lshl_add_u32 v144, s27, 8, v152
	v_ashrrev_i32_e32 v145, 31, v144
	v_cndmask_b32_e64 v128, 0, 1, s[12:13]
	v_cmp_ne_u32_e64 s[44:45], 1, v128
	s_andn2_b64 vcc, exec, s[12:13]
	v_mov_b32_e32 v148, 1.0
	s_cbranch_vccnz .LBB0_642
	v_readlane_b32 s12, v245, 42
	v_readlane_b32 s13, v245, 43
	s_mov_b32 s5, 0x800000
	s_nop 0
	v_lshl_add_u64 v[142:143], v[144:145], 2, s[12:13]
	global_load_dword v128, v[142:143], off
	global_load_dword v174, v[142:143], off offset:64
	global_load_dword v175, v[142:143], off offset:128
	global_load_dword v176, v[142:143], off offset:192
	global_load_dword v177, v[142:143], off offset:512
	global_load_dword v178, v[142:143], off offset:576
	global_load_dword v179, v[142:143], off offset:640
	global_load_dword v180, v[142:143], off offset:704
	s_waitcnt vmcnt(0)
	v_fmamk_f32 v128, v128, 0x3a800000, v154
	v_mul_f32_e32 v142, 0x4b800000, v128
	v_cmp_gt_f32_e32 vcc, s5, v128
	s_nop 1
	v_cndmask_b32_e32 v128, v128, v142, vcc
	v_rsq_f32_e32 v128, v128
	s_nop 0
	v_mul_f32_e32 v142, 0x45800000, v128
	v_cndmask_b32_e32 v148, v128, v142, vcc

;     __device__ __forceinline__ void operator()(const f32x4 (&acc)[2][2][4][2], const Unit& u, int wr, int wc, int fr, int fq) const {
;     ...
;                 const size_t row = (size_t)(row0 + ai * HALF + m * 16);
;                 const float rs = ss ? rsqrtf(ss[row] * (1.f / 1024.f) + 1e-6f) : 1.f;
.LBB0_656:
	s_or_b64 exec, exec, s[12:13]
	s_nop 0
	v_or_b32_e32 v116, 16, v144
	v_ashrrev_i32_e32 v117, 31, v116
	s_and_b64 vcc, exec, s[44:45]
	v_mov_b32_e32 v114, 1.0
	s_cbranch_vccnz .LBB0_658
	v_readlane_b32 s12, v245, 42
	v_readlane_b32 s13, v245, 43
	s_mov_b32 s5, 0x800000
	s_nop 0
	v_lshl_add_u64 v[112:113], v[116:117], 2, s[12:13]
	v_mov_b32_e32 v112, v174
	v_fmamk_f32 v112, v112, 0x3a800000, v154
	v_mul_f32_e32 v113, 0x4b800000, v112
	v_cmp_gt_f32_e32 vcc, s5, v112
	s_nop 1
	v_cndmask_b32_e32 v112, v112, v113, vcc
	v_rsq_f32_e32 v112, v112
	s_nop 0
	v_mul_f32_e32 v113, 0x45800000, v112
	v_cndmask_b32_e32 v114, v112, v113, vcc

;     __device__ __forceinline__ void operator()(const f32x4 (&acc)[2][2][4][2], const Unit& u, int wr, int wc, int fr, int fq) const {
;     ...
;                 const size_t row = (size_t)(row0 + ai * HALF + m * 16);
;                 const float rs = ss ? rsqrtf(ss[row] * (1.f / 1024.f) + 1e-6f) : 1.f;
.LBB0_672:
	s_or_b64 exec, exec, s[12:13]
	s_nop 0
	v_or_b32_e32 v100, 32, v144
	v_ashrrev_i32_e32 v101, 31, v100
	s_and_b64 vcc, exec, s[44:45]
	v_mov_b32_e32 v98, 1.0
	s_cbranch_vccnz .LBB0_674
	v_readlane_b32 s12, v245, 42
	v_readlane_b32 s13, v245, 43
	s_mov_b32 s5, 0x800000
	s_nop 0
	v_lshl_add_u64 v[96:97], v[100:101], 2, s[12:13]
	v_mov_b32_e32 v96, v175
	v_fmamk_f32 v96, v96, 0x3a800000, v154
	v_mul_f32_e32 v97, 0x4b800000, v96
	v_cmp_gt_f32_e32 vcc, s5, v96
	s_nop 1
	v_cndmask_b32_e32 v96, v96, v97, vcc
	v_rsq_f32_e32 v96, v96
	s_nop 0
	v_mul_f32_e32 v97, 0x45800000, v96
	v_cndmask_b32_e32 v98, v96, v97, vcc

;     __device__ __forceinline__ void operator()(const f32x4 (&acc)[2][2][4][2], const Unit& u, int wr, int wc, int fr, int fq) const {
;     ...
;                 const size_t row = (size_t)(row0 + ai * HALF + m * 16);
;                 const float rs = ss ? rsqrtf(ss[row] * (1.f / 1024.f) + 1e-6f) : 1.f;
.LBB0_688:
	s_or_b64 exec, exec, s[12:13]
	s_nop 0
	v_or_b32_e32 v84, 48, v144
	v_ashrrev_i32_e32 v85, 31, v84
	s_and_b64 vcc, exec, s[44:45]
	v_mov_b32_e32 v82, 1.0
	s_cbranch_vccnz .LBB0_690
	v_readlane_b32 s12, v245, 42
	v_readlane_b32 s13, v245, 43
	s_mov_b32 s5, 0x800000
	s_nop 0
	v_lshl_add_u64 v[80:81], v[84:85], 2, s[12:13]
	v_mov_b32_e32 v80, v176
	v_fmamk_f32 v80, v80, 0x3a800000, v154
	v_mul_f32_e32 v81, 0x4b800000, v80
	v_cmp_gt_f32_e32 vcc, s5, v80
	s_nop 1
	v_cndmask_b32_e32 v80, v80, v81, vcc
	v_rsq_f32_e32 v80, v80
	s_nop 0
	v_mul_f32_e32 v81, 0x45800000, v80
	v_cndmask_b32_e32 v82, v80, v81, vcc

;     __device__ __forceinline__ void operator()(const f32x4 (&acc)[2][2][4][2], const Unit& u, int wr, int wc, int fr, int fq) const {
;     ...
;                 const size_t row = (size_t)(row0 + ai * HALF + m * 16);
;                 const float rs = ss ? rsqrtf(ss[row] * (1.f / 1024.f) + 1e-6f) : 1.f;
.LBB0_704:
	s_or_b64 exec, exec, s[12:13]
	s_nop 0
	v_add_u32_e32 v68, 0x80, v144
	v_ashrrev_i32_e32 v69, 31, v68
	s_and_b64 vcc, exec, s[44:45]
	v_mov_b32_e32 v66, 1.0
	s_cbranch_vccnz .LBB0_706
	v_readlane_b32 s12, v245, 42
	v_readlane_b32 s13, v245, 43
	s_mov_b32 s5, 0x800000
	s_nop 0
	v_lshl_add_u64 v[64:65], v[68:69], 2, s[12:13]
	v_mov_b32_e32 v64, v177
	v_fmamk_f32 v64, v64, 0x3a800000, v154
	v_mul_f32_e32 v65, 0x4b800000, v64
	v_cmp_gt_f32_e32 vcc, s5, v64
	s_nop 1
	v_cndmask_b32_e32 v64, v64, v65, vcc
	v_rsq_f32_e32 v64, v64
	s_nop 0
	v_mul_f32_e32 v65, 0x45800000, v64
	v_cndmask_b32_e32 v66, v64, v65, vcc

;     __device__ __forceinline__ void operator()(const f32x4 (&acc)[2][2][4][2], const Unit& u, int wr, int wc, int fr, int fq) const {
;     ...
;                 const size_t row = (size_t)(row0 + ai * HALF + m * 16);
;                 const float rs = ss ? rsqrtf(ss[row] * (1.f / 1024.f) + 1e-6f) : 1.f;
.LBB0_720:
	s_or_b64 exec, exec, s[12:13]
	s_nop 0
	v_add_u32_e32 v52, 0x90, v144
	v_ashrrev_i32_e32 v53, 31, v52
	s_and_b64 vcc, exec, s[44:45]
	v_mov_b32_e32 v50, 1.0
	s_cbranch_vccnz .LBB0_722
	v_readlane_b32 s12, v245, 42
	v_readlane_b32 s13, v245, 43
	s_mov_b32 s5, 0x800000
	s_nop 0
	v_lshl_add_u64 v[48:49], v[52:53], 2, s[12:13]
	v_mov_b32_e32 v48, v178
	v_fmamk_f32 v48, v48, 0x3a800000, v154
	v_mul_f32_e32 v49, 0x4b800000, v48
	v_cmp_gt_f32_e32 vcc, s5, v48
	s_nop 1
	v_cndmask_b32_e32 v48, v48, v49, vcc
	v_rsq_f32_e32 v48, v48
	s_nop 0
	v_mul_f32_e32 v49, 0x45800000, v48
	v_cndmask_b32_e32 v50, v48, v49, vcc

;     __device__ __forceinline__ void operator()(const f32x4 (&acc)[2][2][4][2], const Unit& u, int wr, int wc, int fr, int fq) const {
;     ...
;                 const size_t row = (size_t)(row0 + ai * HALF + m * 16);
;                 const float rs = ss ? rsqrtf(ss[row] * (1.f / 1024.f) + 1e-6f) : 1.f;
.LBB0_736:
	s_or_b64 exec, exec, s[12:13]
	s_nop 0
	v_add_u32_e32 v36, 0xa0, v144
	v_ashrrev_i32_e32 v37, 31, v36
	s_and_b64 vcc, exec, s[44:45]
	v_mov_b32_e32 v34, 1.0
	s_cbranch_vccnz .LBB0_738
	v_readlane_b32 s12, v245, 42
	v_readlane_b32 s13, v245, 43
	s_mov_b32 s5, 0x800000
	s_nop 0
	v_lshl_add_u64 v[32:33], v[36:37], 2, s[12:13]
	v_mov_b32_e32 v32, v179
	v_fmamk_f32 v32, v32, 0x3a800000, v154
	v_mul_f32_e32 v33, 0x4b800000, v32
	v_cmp_gt_f32_e32 vcc, s5, v32
	s_nop 1
	v_cndmask_b32_e32 v32, v32, v33, vcc
	v_rsq_f32_e32 v32, v32
	s_nop 0
	v_mul_f32_e32 v33, 0x45800000, v32
	v_cndmask_b32_e32 v34, v32, v33, vcc

;     __device__ __forceinline__ void operator()(const f32x4 (&acc)[2][2][4][2], const Unit& u, int wr, int wc, int fr, int fq) const {
;     ...
;                 const size_t row = (size_t)(row0 + ai * HALF + m * 16);
;                 const float rs = ss ? rsqrtf(ss[row] * (1.f / 1024.f) + 1e-6f) : 1.f;
.LBB0_752:
	s_or_b64 exec, exec, s[12:13]
	s_nop 0
	v_add_u32_e32 v20, 0xb0, v144
	v_ashrrev_i32_e32 v21, 31, v20
	s_and_b64 vcc, exec, s[44:45]
	v_mov_b32_e32 v18, 1.0
	s_cbranch_vccnz .LBB0_754
	v_readlane_b32 s12, v245, 42
	v_readlane_b32 s13, v245, 43
	s_mov_b32 s5, 0x800000
	s_nop 0
	v_lshl_add_u64 v[16:17], v[20:21], 2, s[12:13]
	v_mov_b32_e32 v16, v180
	v_fmamk_f32 v16, v16, 0x3a800000, v154
	v_mul_f32_e32 v17, 0x4b800000, v16
	v_cmp_gt_f32_e32 vcc, s5, v16
	s_nop 1
	v_cndmask_b32_e32 v16, v16, v17, vcc
	v_rsq_f32_e32 v16, v16
	s_nop 0
	v_mul_f32_e32 v17, 0x45800000, v16
	v_cndmask_b32_e32 v18, v16, v17, vcc
